# gating phase: the four W_s fragment loads issued together with the V tile loads instead of one exposed load per k-step
# speedup vs baseline: 1.0043x; 1.0043x over previous
.LBB0_2542:
	s_or_b64 exec, exec, s[34:35]
	s_and_b32 s12, s31, 0x380
	v_add_u32_e32 v4, s38, v55
	s_lshl_b32 s34, s12, 1
	s_mov_b32 s35, s13
	v_ashrrev_i32_e32 v5, 31, v4
	v_lshl_add_u64 v[16:17], v[42:43], 0, s[34:35]
	v_lshlrev_b64 v[4:5], 11, v[4:5]
	v_lshl_add_u64 v[4:5], v[16:17], 0, v[4:5]
	s_waitcnt vmcnt(0) lgkmcnt(0)
	s_barrier
	global_load_dwordx4 v[4:7], v[4:5], off
	v_add_u32_e32 v8, s38, v57
	v_ashrrev_i32_e32 v9, 31, v8
	v_lshlrev_b64 v[8:9], 11, v[8:9]
	v_lshl_add_u64 v[8:9], v[16:17], 0, v[8:9]
	global_load_dwordx4 v[8:11], v[8:9], off
	v_add_u32_e32 v12, s38, v59
	v_ashrrev_i32_e32 v13, 31, v12
	v_lshlrev_b64 v[12:13], 11, v[12:13]
	v_lshl_add_u64 v[12:13], v[16:17], 0, v[12:13]
	global_load_dwordx4 v[12:15], v[12:13], off
	v_add_u32_e32 v18, s38, v61
	v_ashrrev_i32_e32 v19, 31, v18
	v_lshlrev_b64 v[18:19], 11, v[18:19]
	v_lshl_add_u64 v[16:17], v[16:17], 0, v[18:19]
	global_load_dwordx4 v[16:19], v[16:17], off
	ds_read_b32 v2, v56 offset:34816
	v_lshl_add_u64 v[20:21], v[44:45], 0, s[12:13]
	v_lshlrev_b64 v[20:21], 8, v[20:21]
	v_lshl_add_u64 v[52:53], v[46:47], 0, v[20:21]
	global_load_dwordx4 v[112:115], v[52:53], off
	global_load_dwordx4 v[116:119], v[52:53], off offset:64
	global_load_dwordx4 v[120:123], v[52:53], off offset:128
	global_load_dwordx4 v[124:127], v[52:53], off offset:192
	v_mov_b32_e32 v36, 0
	v_mov_b32_e32 v37, 0
	v_mov_b32_e32 v38, 0
	v_mov_b32_e32 v39, 0
	s_andn2_b64 vcc, exec, s[24:25]
	v_mov_b32_e32 v34, 0
	v_mov_b32_e32 v35, 0
	s_waitcnt vmcnt(7)
	v_lshlrev_b32_e32 v20, 16, v4
	v_and_b32_e32 v21, 0xffff0000, v4
	v_lshlrev_b32_e32 v4, 16, v5
	v_and_b32_e32 v5, 0xffff0000, v5
	v_lshlrev_b32_e32 v22, 16, v6
	v_and_b32_e32 v23, 0xffff0000, v6
	v_lshlrev_b32_e32 v6, 16, v7
	v_and_b32_e32 v7, 0xffff0000, v7
	s_waitcnt lgkmcnt(0)
	v_pk_mul_f32 v[20:21], v[2:3], v[20:21] op_sel_hi:[0,1]
	v_pk_mul_f32 v[30:31], v[2:3], v[4:5] op_sel_hi:[0,1]
	v_pk_mul_f32 v[22:23], v[2:3], v[22:23] op_sel_hi:[0,1]
	v_pk_mul_f32 v[32:33], v[2:3], v[6:7] op_sel_hi:[0,1]
	v_cvt_pk_bf16_f32 v4, v20, v21
	v_cvt_pk_bf16_f32 v5, v30, v31
	v_cvt_pk_bf16_f32 v6, v22, v23
	v_cvt_pk_bf16_f32 v7, v32, v33
	ds_write_b128 v64, v[4:7]
	ds_read_b32 v2, v58 offset:34816
	s_waitcnt vmcnt(6)
	v_lshlrev_b32_e32 v24, 16, v8
	v_and_b32_e32 v25, 0xffff0000, v8
	v_lshlrev_b32_e32 v8, 16, v9
	v_and_b32_e32 v9, 0xffff0000, v9
	v_lshlrev_b32_e32 v26, 16, v10
	v_and_b32_e32 v27, 0xffff0000, v10
	v_lshlrev_b32_e32 v10, 16, v11
	v_and_b32_e32 v11, 0xffff0000, v11
	s_waitcnt lgkmcnt(0)
	v_pk_mul_f32 v[4:5], v[2:3], v[24:25] op_sel_hi:[0,1]
	v_pk_mul_f32 v[6:7], v[2:3], v[8:9] op_sel_hi:[0,1]
	v_pk_mul_f32 v[8:9], v[2:3], v[26:27] op_sel_hi:[0,1]
	v_pk_mul_f32 v[10:11], v[2:3], v[10:11] op_sel_hi:[0,1]
	v_cvt_pk_bf16_f32 v4, v4, v5
	v_cvt_pk_bf16_f32 v5, v6, v7
	v_cvt_pk_bf16_f32 v6, v8, v9
	v_cvt_pk_bf16_f32 v7, v10, v11
	ds_write_b128 v65, v[4:7]
	ds_read_b32 v2, v60 offset:34816
	s_waitcnt vmcnt(5)
	v_lshlrev_b32_e32 v28, 16, v12
	v_and_b32_e32 v29, 0xffff0000, v12
	v_lshlrev_b32_e32 v12, 16, v13
	v_and_b32_e32 v13, 0xffff0000, v13
	v_lshlrev_b32_e32 v20, 16, v14
	v_and_b32_e32 v21, 0xffff0000, v14
	v_lshlrev_b32_e32 v14, 16, v15
	v_and_b32_e32 v15, 0xffff0000, v15
	s_waitcnt lgkmcnt(0)
	v_pk_mul_f32 v[4:5], v[2:3], v[28:29] op_sel_hi:[0,1]
	v_pk_mul_f32 v[6:7], v[2:3], v[12:13] op_sel_hi:[0,1]
	v_pk_mul_f32 v[12:13], v[2:3], v[20:21] op_sel_hi:[0,1]
	v_pk_mul_f32 v[14:15], v[2:3], v[14:15] op_sel_hi:[0,1]
	v_cvt_pk_bf16_f32 v4, v4, v5
	v_cvt_pk_bf16_f32 v5, v6, v7
	v_cvt_pk_bf16_f32 v6, v12, v13
	v_cvt_pk_bf16_f32 v7, v14, v15
	ds_write_b128 v66, v[4:7]
	ds_read_b32 v2, v62 offset:34816
	s_waitcnt vmcnt(4)
	v_lshlrev_b32_e32 v8, 16, v16
	v_and_b32_e32 v9, 0xffff0000, v16
	v_lshlrev_b32_e32 v10, 16, v17
	v_and_b32_e32 v11, 0xffff0000, v17
	v_lshlrev_b32_e32 v4, 16, v18
	v_and_b32_e32 v5, 0xffff0000, v18
	v_lshlrev_b32_e32 v6, 16, v19
	v_and_b32_e32 v7, 0xffff0000, v19
	s_waitcnt lgkmcnt(0)
	v_pk_mul_f32 v[8:9], v[2:3], v[8:9] op_sel_hi:[0,1]
	v_pk_mul_f32 v[10:11], v[2:3], v[10:11] op_sel_hi:[0,1]
	v_pk_mul_f32 v[12:13], v[2:3], v[4:5] op_sel_hi:[0,1]
	v_pk_mul_f32 v[14:15], v[2:3], v[6:7] op_sel_hi:[0,1]
	v_cvt_pk_bf16_f32 v4, v8, v9
	v_cvt_pk_bf16_f32 v5, v10, v11
	v_cvt_pk_bf16_f32 v6, v12, v13
	v_cvt_pk_bf16_f32 v7, v14, v15
	ds_write_b128 v67, v[4:7]
	v_mov_b32_e32 v28, 0
	v_mov_b32_e32 v29, 0
	v_mov_b32_e32 v30, 0
	v_mov_b32_e32 v31, 0
	v_mov_b32_e32 v24, 0
	v_mov_b32_e32 v25, 0
	v_mov_b32_e32 v26, 0
	v_mov_b32_e32 v27, 0
	v_mov_b32_e32 v20, 0
	v_mov_b32_e32 v21, 0
	v_mov_b32_e32 v22, 0
	v_mov_b32_e32 v23, 0
	v_mov_b32_e32 v12, 0
	v_mov_b32_e32 v13, 0
	v_mov_b32_e32 v14, 0
	v_mov_b32_e32 v15, 0
	v_mov_b32_e32 v16, 0
	v_mov_b32_e32 v17, 0
	v_mov_b32_e32 v18, 0
	v_mov_b32_e32 v19, 0
	v_mov_b32_e32 v8, 0
	v_mov_b32_e32 v9, 0
	v_mov_b32_e32 v10, 0
	v_mov_b32_e32 v11, 0
	v_mov_b32_e32 v4, 0
	v_mov_b32_e32 v5, 0
	v_mov_b32_e32 v6, 0
	v_mov_b32_e32 v7, 0
	v_mov_b32_e32 v32, 0
	v_mov_b32_e32 v33, 0
	s_waitcnt lgkmcnt(0)
	s_barrier
	s_cbranch_vccnz .LBB0_2546
	ds_read_b64_tr_b16 v[4:5], v63
	ds_read_b64_tr_b16 v[6:7], v63 offset:1088
	ds_read_b64_tr_b16 v[10:11], v63 offset:1120
	ds_read_b64_tr_b16 v[8:9], v63 offset:32
	ds_read_b64_tr_b16 v[12:13], v63 offset:64
	ds_read_b64_tr_b16 v[16:17], v63 offset:96
	ds_read_b64_tr_b16 v[14:15], v63 offset:1152
	ds_read_b64_tr_b16 v[18:19], v63 offset:1184
	s_waitcnt vmcnt(0) lgkmcnt(6)
	v_mfma_f32_16x16x32_bf16 v[28:31], v[4:7], v[112:115], 0
	ds_read_b64_tr_b16 v[4:5], v63 offset:128
	s_waitcnt lgkmcnt(5)
	v_mfma_f32_16x16x32_bf16 v[24:27], v[8:11], v[112:115], 0
	ds_read_b64_tr_b16 v[6:7], v63 offset:1216
	ds_read_b64_tr_b16 v[10:11], v63 offset:1248
	ds_read_b64_tr_b16 v[8:9], v63 offset:160
	ds_read_b64_tr_b16 v[36:37], v63 offset:192
	ds_read_b64_tr_b16 v[68:69], v63 offset:224
	ds_read_b64_tr_b16 v[38:39], v63 offset:1280
	ds_read_b64_tr_b16 v[70:71], v63 offset:1312
	s_waitcnt lgkmcnt(9)
	v_mfma_f32_16x16x32_bf16 v[20:23], v[12:15], v[112:115], 0
	s_waitcnt lgkmcnt(8)
	v_mfma_f32_16x16x32_bf16 v[12:15], v[16:19], v[112:115], 0
	s_waitcnt lgkmcnt(6)
	v_mfma_f32_16x16x32_bf16 v[16:19], v[4:7], v[112:115], 0
	s_waitcnt lgkmcnt(1)
	v_mfma_f32_16x16x32_bf16 v[4:7], v[36:39], v[112:115], 0
	s_waitcnt lgkmcnt(0)
	v_mfma_f32_16x16x32_bf16 v[36:39], v[68:71], v[112:115], 0
	v_mfma_f32_16x16x32_bf16 v[8:11], v[8:11], v[112:115], 0
	s_nop 6
	v_mov_b32_e32 v32, v36
	v_mov_b32_e32 v33, v37
	v_mov_b32_e32 v34, v38
	v_mov_b32_e32 v35, v39
	s_andn2_b64 vcc, exec, s[26:27]
	s_cbranch_vccz .LBB0_2547

.LBB0_2545:
	s_nop 0
	ds_read_b64_tr_b16 v[70:71], v63 offset:18496
	ds_read_b64_tr_b16 v[68:69], v63 offset:17408
	ds_read_b64_tr_b16 v[72:73], v63 offset:17440
	ds_read_b64_tr_b16 v[74:75], v63 offset:18528
	s_waitcnt vmcnt(0) lgkmcnt(2)
	v_mfma_f32_16x16x32_bf16 v[28:31], v[68:71], v[120:123], v[28:31]
	ds_read_b64_tr_b16 v[68:69], v63 offset:17472
	ds_read_b64_tr_b16 v[70:71], v63 offset:18560
	s_waitcnt lgkmcnt(2)
	v_mfma_f32_16x16x32_bf16 v[24:27], v[72:75], v[120:123], v[24:27]
	s_waitcnt lgkmcnt(0)
	v_mfma_f32_16x16x32_bf16 v[20:23], v[68:71], v[120:123], v[20:23]
	ds_read_b64_tr_b16 v[68:69], v63 offset:17504
	ds_read_b64_tr_b16 v[70:71], v63 offset:18592
	s_waitcnt lgkmcnt(0)
	v_mfma_f32_16x16x32_bf16 v[12:15], v[68:71], v[120:123], v[12:15]
	ds_read_b64_tr_b16 v[68:69], v63 offset:17536
	ds_read_b64_tr_b16 v[70:71], v63 offset:18624
	s_waitcnt lgkmcnt(0)
	v_mfma_f32_16x16x32_bf16 v[16:19], v[68:71], v[120:123], v[16:19]
	ds_read_b64_tr_b16 v[68:69], v63 offset:17568
	ds_read_b64_tr_b16 v[70:71], v63 offset:18656
	s_waitcnt lgkmcnt(0)
	v_mfma_f32_16x16x32_bf16 v[8:11], v[68:71], v[120:123], v[8:11]
	ds_read_b64_tr_b16 v[68:69], v63 offset:17600
	ds_read_b64_tr_b16 v[70:71], v63 offset:18688
	s_waitcnt lgkmcnt(0)
	v_mfma_f32_16x16x32_bf16 v[4:7], v[68:71], v[120:123], v[4:7]
	ds_read_b64_tr_b16 v[68:69], v63 offset:17632
	ds_read_b64_tr_b16 v[70:71], v63 offset:18720
	s_waitcnt lgkmcnt(0)
	v_mfma_f32_16x16x32_bf16 v[32:35], v[68:71], v[120:123], v[32:35]
	s_andn2_b64 vcc, exec, s[36:37]
	s_cbranch_vccnz .LBB0_2539
	s_branch .LBB0_2549

.LBB0_2547:
	ds_read_b64_tr_b16 v[70:71], v63 offset:9792
	ds_read_b64_tr_b16 v[68:69], v63 offset:8704
	ds_read_b64_tr_b16 v[72:73], v63 offset:8736
	ds_read_b64_tr_b16 v[74:75], v63 offset:9824
	s_waitcnt vmcnt(0) lgkmcnt(2)
	v_mfma_f32_16x16x32_bf16 v[28:31], v[68:71], v[116:119], v[28:31]
	ds_read_b64_tr_b16 v[68:69], v63 offset:8768
	ds_read_b64_tr_b16 v[70:71], v63 offset:9856
	s_waitcnt lgkmcnt(2)
	v_mfma_f32_16x16x32_bf16 v[24:27], v[72:75], v[116:119], v[24:27]
	s_waitcnt lgkmcnt(0)
	v_mfma_f32_16x16x32_bf16 v[20:23], v[68:71], v[116:119], v[20:23]
	ds_read_b64_tr_b16 v[68:69], v63 offset:8800
	ds_read_b64_tr_b16 v[70:71], v63 offset:9888
	s_waitcnt lgkmcnt(0)
	v_mfma_f32_16x16x32_bf16 v[12:15], v[68:71], v[116:119], v[12:15]
	ds_read_b64_tr_b16 v[68:69], v63 offset:8832
	ds_read_b64_tr_b16 v[70:71], v63 offset:9920
	s_waitcnt lgkmcnt(0)
	v_mfma_f32_16x16x32_bf16 v[16:19], v[68:71], v[116:119], v[16:19]
	ds_read_b64_tr_b16 v[68:69], v63 offset:8864
	ds_read_b64_tr_b16 v[70:71], v63 offset:9952
	s_waitcnt lgkmcnt(0)
	v_mfma_f32_16x16x32_bf16 v[8:11], v[68:71], v[116:119], v[8:11]
	ds_read_b64_tr_b16 v[68:69], v63 offset:8896
	ds_read_b64_tr_b16 v[70:71], v63 offset:9984
	s_waitcnt lgkmcnt(0)
	v_mfma_f32_16x16x32_bf16 v[4:7], v[68:71], v[116:119], v[4:7]
	ds_read_b64_tr_b16 v[68:69], v63 offset:8928
	ds_read_b64_tr_b16 v[70:71], v63 offset:10016
	s_waitcnt lgkmcnt(0)
	v_mfma_f32_16x16x32_bf16 v[32:35], v[68:71], v[116:119], v[36:39]
	s_andn2_b64 vcc, exec, s[28:29]
	s_cbranch_vccz .LBB0_2545

.LBB0_2549:
	ds_read_b64_tr_b16 v[70:71], v63 offset:27200
	ds_read_b64_tr_b16 v[68:69], v63 offset:26112
	ds_read_b64_tr_b16 v[72:73], v63 offset:26144
	ds_read_b64_tr_b16 v[74:75], v63 offset:27232
	s_waitcnt vmcnt(0) lgkmcnt(2)
	v_mfma_f32_16x16x32_bf16 v[28:31], v[68:71], v[124:127], v[28:31]
	ds_read_b64_tr_b16 v[68:69], v63 offset:26176
	ds_read_b64_tr_b16 v[70:71], v63 offset:27264
	s_waitcnt lgkmcnt(2)
	v_mfma_f32_16x16x32_bf16 v[24:27], v[72:75], v[124:127], v[24:27]
	s_waitcnt lgkmcnt(0)
	v_mfma_f32_16x16x32_bf16 v[20:23], v[68:71], v[124:127], v[20:23]
	ds_read_b64_tr_b16 v[68:69], v63 offset:26208
	ds_read_b64_tr_b16 v[70:71], v63 offset:27296
	s_waitcnt lgkmcnt(0)
	v_mfma_f32_16x16x32_bf16 v[12:15], v[68:71], v[124:127], v[12:15]
	ds_read_b64_tr_b16 v[68:69], v63 offset:26240
	ds_read_b64_tr_b16 v[70:71], v63 offset:27328
	s_waitcnt lgkmcnt(0)
	v_mfma_f32_16x16x32_bf16 v[16:19], v[68:71], v[124:127], v[16:19]
	ds_read_b64_tr_b16 v[68:69], v63 offset:26272
	ds_read_b64_tr_b16 v[70:71], v63 offset:27360
	s_waitcnt lgkmcnt(0)
	v_mfma_f32_16x16x32_bf16 v[8:11], v[68:71], v[124:127], v[8:11]
	ds_read_b64_tr_b16 v[68:69], v63 offset:26304
	ds_read_b64_tr_b16 v[70:71], v63 offset:27392
	s_waitcnt lgkmcnt(0)
	v_mfma_f32_16x16x32_bf16 v[4:7], v[68:71], v[124:127], v[4:7]
	ds_read_b64_tr_b16 v[68:69], v63 offset:26336
	ds_read_b64_tr_b16 v[70:71], v63 offset:27424
	s_waitcnt lgkmcnt(0)
	v_mfma_f32_16x16x32_bf16 v[32:35], v[68:71], v[124:127], v[32:35]
	s_branch .LBB0_2539
